# A + P8 workgroups start staggered in 8 groups of 0.9us so their H store bursts do not coincide
# baseline (speedup 1.0000x reference)
; __global__ void __launch_bounds__(NTHREADS, 2) fwd_kernel(Params p) {
;     ...
;     {
;         pg8::Gemm g{(const bf16*)(ws + WS_X1B), (const bf16*)(ws + WS_WF1), M, FF, DM, wave}; pg8::StaticOrder S; S.init(M, FF, G, bid);
;         pg8::EpiBf16<2> E{(bf16*)(ws + WS_H), FF};
;         pg8::gemm_phase<pg8::EpiBf16<2>, pg8::StaticOrder, true, true>(lds, g, S, E);
;     }
.LBB0_4089:
	s_or_b64 exec, exec, s[4:5]
	s_add_u32 s20, s82, 0xe000000
	s_addc_u32 s21, s83, 0
	v_readlane_b32 s4, v243, 2
	v_mov_b32_e32 v8, v220
	s_cmpk_gt_i32 s4, 0x7ff
	s_waitcnt lgkmcnt(0)
	s_barrier
	s_cbranch_scc1 .LBB0_4113
	v_readlane_b32 s4, v243, 2
	s_bfe_u32 s4, s4, 0x30003
	s_cmp_eq_u32 s4, 0
	s_cbranch_scc1 .Lp8_nodelay
.Lp8_delay:
	s_sleep 28
	s_sleep 0
	s_sub_u32 s4, s4, 1
	s_cmp_lg_u32 s4, 0
	s_cbranch_scc1 .Lp8_delay
.Lp8_nodelay:
	s_lshr_b32 s4, s33, 29
	v_readlane_b32 s5, v243, 2
	s_add_i32 s7, s5, s4
	s_and_b32 s4, s7, -8
	s_sub_i32 s8, s5, s4
	s_cmp_gt_i32 s8, -1
	s_cbranch_scc0 .LBB0_4092
	s_lshl_b32 s6, s8, 8
	s_cbranch_execz .LBB0_4093
	s_branch .LBB0_4094
